# the one cooperative-groups grid.sync after the prologue replaced by a counter barrier on a per-call-zeroed control word (release write-back, one add per workgroup, poll, L1 invalidate)
# speedup vs baseline: 1.0047x; 1.0047x over previous
; __global__ void __launch_bounds__(NTHR, 2) fwd_kernel(Args a) {
;     ...
;     grid.sync();
.LBB0_219:
	s_or_b64 exec, exec, s[0:1]
	v_lshrrev_b32_e32 v1, 20, v0
	v_lshrrev_b32_e32 v0, 10, v0
	v_or_b32_e32 v0, v0, v1
	s_movk_i32 s0, 0x3ff
	v_and_or_b32 v0, v0, s0, v174
	v_cmp_eq_u32_e32 vcc, 0, v0
	s_waitcnt lgkmcnt(0)
	s_barrier
	s_and_saveexec_b64 s[0:1], vcc
	v_readlane_b32 s12, v250, 0
	v_readlane_b32 s13, v250, 1
	v_readlane_b32 s14, v250, 2
	v_readlane_b32 s15, v250, 3
	v_readlane_b32 s16, v250, 4
	v_readlane_b32 s17, v250, 5
	v_readlane_b32 s18, v250, 6
	v_readlane_b32 s19, v250, 7
	s_cbranch_execz .LBB0_229
	buffer_wbl2 sc1
	s_waitcnt vmcnt(0)
	v_mov_b32_e32 v2, 0xa000
	v_mov_b32_e32 v3, 1
	s_nop 4
	global_atomic_add v2, v3, s[16:17]
.Lgs_poll:
	s_sleep 1
	global_load_dword v0, v2, s[16:17] sc1
	s_waitcnt vmcnt(0)
	v_cmp_ne_u32_e32 vcc, 0x100, v0
	s_cbranch_vccnz .Lgs_poll
	buffer_inv sc1
	s_waitcnt vmcnt(0)
